# GLA output stores in saddr form with one running 32-bit offset; group-A release moved ahead of the store / convert blocks
# speedup vs baseline: 1.0106x; 1.0006x over previous
; __device__ __forceinline__ unsigned pk2(float lo, float hi) { f32x2_t v = {lo, hi}; bf16x2_t b = __builtin_convertvector(v, bf16x2_t); return __builtin_bit_cast(unsigned, b); }
; #define LAS __attribute__((address_space(3)))
; __device__ __forceinline__ f32x16 mma32(bf16x8 a, bf16x8 b, f32x16 c) { return __builtin_amdgcn_mfma_f32_32x32x16_bf16(a, b, c, 0, 0, 0); }
; #define LDS_WAIT() asm volatile("s_waitcnt lgkmcnt(0)" ::: "memory")
; __device__ __forceinline__ void delta_scan_task(const P& p, int l, int s, int h, int sl, LAS unsigned char* ldsw, int lane) {
;     ...
;         for (int ti = 0; ti < 2; ++ti) {
; #pragma unroll
;             for (int g = 0; g < 4; ++g) { const f32x4v ub4 = FRAGF4(bufA, 32 + ti * 4 + g, lane); u[ti][4 * g] = ub4.x; u[ti][4 * g + 1] = ub4.y; u[ti][4 * g + 2] = ub4.z; u[ti][4 * g + 3] = ub4.w; }
;             o[ti] = zero16();
; #pragma unroll
;             for (int ks = 0; ks < 8; ++ks) {
;                 const bf16x8 b = *(const LAS bf16x8*)(ST + r * 136 + 16 * ks + 8 * hh);
;                 u[ti] = mma32(FRAG16(bufA, ti * 8 + ks, lane), b, u[ti]); o[ti] = mma32(FRAG16(bufA, 16 + ti * 8 + ks, lane), b, o[ti]);
;             }
;         }
; #pragma unroll
;         for (int ti = 0; ti < 2; ++ti)
; #pragma unroll
;             for (int g = 0; g < 4; ++g) { u32x2v w; w.x = pk2(u[ti][4 * g], u[ti][4 * g + 1]); w.y = pk2(u[ti][4 * g + 2], u[ti][4 * g + 3]); *(LAS u32x2v*)(UT + r * 72 + 32 * ti + 8 * g + 4 * hh) = w; }
;         LDS_WAIT();
;         if (SCAN_LOADERS) { if (lane == 0) FL[3] = (unsigned)n + 1u; lds_wait_ge(FL + 2, (unsigned)n + 1u, FL + 5); }
.Ldp1_done:
	s_waitcnt lgkmcnt(0)
	ds_read_b128 v[114:117], v209 offset:53248
	ds_read_b128 v[118:121], v209 offset:54272
	ds_read_b128 v[122:125], v209 offset:55296
	ds_read_b128 v[126:129], v209 offset:56320
	ds_read_b128 v[236:239], v209 offset:24576
	ds_read_b128 v[240:243], v209 offset:40960
	ds_read_b128 v[244:247], v209 offset:25600
	ds_read_b128 v[168:171], v209 offset:41984
	ds_read_b128 v[232:235], v209 offset:26624
	s_waitcnt lgkmcnt(4)
	v_mfma_f32_32x32x16_bf16 v[114:129], v[236:239], v[70:73], v[114:129]
	ds_read_b128 v[236:239], v209 offset:43008
	s_waitcnt lgkmcnt(4)
	v_mfma_f32_32x32x16_bf16 v[66:81], v[240:243], v[70:73], 0
	ds_read_b128 v[240:243], v209 offset:27648
	s_waitcnt lgkmcnt(4)
	v_mfma_f32_32x32x16_bf16 v[114:129], v[244:247], v[130:133], v[114:129]
	ds_read_b128 v[244:247], v209 offset:44032
	s_waitcnt lgkmcnt(4)
	v_mfma_f32_32x32x16_bf16 v[66:81], v[168:171], v[130:133], v[66:81]
	ds_read_b128 v[168:171], v209 offset:28672
	s_waitcnt lgkmcnt(4)
	v_mfma_f32_32x32x16_bf16 v[114:129], v[232:235], v[212:215], v[114:129]
	ds_read_b128 v[232:235], v209 offset:45056
	s_waitcnt lgkmcnt(4)
	v_mfma_f32_32x32x16_bf16 v[66:81], v[236:239], v[212:215], v[66:81]
	ds_read_b128 v[236:239], v209 offset:29696
	s_waitcnt lgkmcnt(4)
	v_mfma_f32_32x32x16_bf16 v[114:129], v[240:243], v[134:137], v[114:129]
	ds_read_b128 v[240:243], v209 offset:46080
	s_waitcnt lgkmcnt(4)
	v_mfma_f32_32x32x16_bf16 v[66:81], v[244:247], v[134:137], v[66:81]
	ds_read_b128 v[244:247], v209 offset:30720
	s_waitcnt lgkmcnt(4)
	v_mfma_f32_32x32x16_bf16 v[114:129], v[168:171], v[216:219], v[114:129]
	ds_read_b128 v[168:171], v209 offset:47104
	s_waitcnt lgkmcnt(4)
	v_mfma_f32_32x32x16_bf16 v[66:81], v[232:235], v[216:219], v[66:81]
	ds_read_b128 v[232:235], v209 offset:31744
	s_waitcnt lgkmcnt(4)
	v_mfma_f32_32x32x16_bf16 v[114:129], v[236:239], v[220:223], v[114:129]
	ds_read_b128 v[236:239], v209 offset:48128
	s_waitcnt lgkmcnt(4)
	v_mfma_f32_32x32x16_bf16 v[66:81], v[240:243], v[220:223], v[66:81]
	s_waitcnt lgkmcnt(3)
	v_mfma_f32_32x32x16_bf16 v[114:129], v[244:247], v[224:227], v[114:129]
	s_waitcnt lgkmcnt(2)
	v_mfma_f32_32x32x16_bf16 v[66:81], v[168:171], v[224:227], v[66:81]
	s_waitcnt lgkmcnt(1)
	v_mfma_f32_32x32x16_bf16 v[114:129], v[232:235], v[228:231], v[114:129]
	s_waitcnt lgkmcnt(0)
	v_mfma_f32_32x32x16_bf16 v[66:81], v[236:239], v[228:231], v[66:81]
	s_and_saveexec_b64 s[8:9], s[0:1]
	v_mov_b32_e32 v255, s34
	ds_write_b32 v163, v255 offset:13324
	s_or_b64 exec, exec, s[8:9]
	s_nop 7
	s_nop 7
	v_add_u32_e32 v130, v195, v140
	v_add_u32_e32 v131, 0x2000, v130
	v_cvt_pk_bf16_f32 v236, v98, v99
	v_cvt_pk_bf16_f32 v237, v100, v101
	v_cvt_pk_bf16_f32 v238, v102, v103
	v_cvt_pk_bf16_f32 v239, v104, v105
	ds_write2_b64 v131, v[236:237], v[238:239] offset0:64 offset1:66
	v_cvt_pk_bf16_f32 v240, v106, v107
	v_cvt_pk_bf16_f32 v241, v108, v109
	v_cvt_pk_bf16_f32 v242, v110, v111
	v_cvt_pk_bf16_f32 v243, v112, v113
	ds_write2_b64 v131, v[240:241], v[242:243] offset0:68 offset1:70
	v_cvt_pk_bf16_f32 v236, v114, v115
	v_cvt_pk_bf16_f32 v237, v116, v117
	v_cvt_pk_bf16_f32 v238, v118, v119
	v_cvt_pk_bf16_f32 v239, v120, v121
	ds_write2_b64 v131, v[236:237], v[238:239] offset0:72 offset1:74
	v_cvt_pk_bf16_f32 v240, v122, v123
	v_cvt_pk_bf16_f32 v241, v124, v125
	v_cvt_pk_bf16_f32 v242, v126, v127
	v_cvt_pk_bf16_f32 v243, v128, v129
	ds_write2_b64 v131, v[240:241], v[242:243] offset0:76 offset1:78
	s_waitcnt lgkmcnt(0)
	s_and_saveexec_b64 s[8:9], s[0:1]
	s_or_b64 exec, exec, s[8:9]
	ds_read_b32 v98, v163 offset:13320
	s_waitcnt lgkmcnt(0)
	v_cmp_lt_u32_e32 vcc, s7, v98
	s_cbranch_vccnz .LBB0_1515
	s_mov_b32 s4, 1
	s_branch .LBB0_1507

; #define LAS __attribute__((address_space(3)))
; __device__ __forceinline__ void gla_scan_task(const P& p, int l, int s, int h, int sl, LAS unsigned char* ldsw, int lane) {
;     LAS bf16* ST = (LAS bf16*)ldsw;
;     LAS unsigned char* bufA = ldsw + 16384; LAS unsigned char* bufB = ldsw + 16384 + 28 * 1024;
;     const int r = lane & 31, hh = lane >> 5;
;     f32x16 S[4];
; #pragma unroll
;     for (int d = 0; d < 4; ++d) S[d] = zero16();
;     volatile LAS unsigned* FL = (volatile LAS unsigned*)(ldsw + SCAN_FLAGS_OFF);
;     if (!SCAN_LOADERS) { const int ch0 = (s * 64 + 0) * 4 + h; gla_issue_A(p, ch0, sl, bufA, r, hh); gla_issue_B(p, ch0, bufB, r, hh); }
.LBB0_1518:
	s_and_b64 vcc, exec, s[8:9]
	s_cbranch_vccz .LBB0_1443
	s_bfe_u32 s15, s37, 0x20003
	s_lshl_b32 s4, s37, 5
	v_readlane_b32 s64, v254, 3
	s_ashr_i32 s6, s37, 5
	s_and_b32 s14, s4, 0xe0
	s_lshl_b32 s4, s15, 10
	v_readlane_b32 s70, v254, 9
	v_readlane_b32 s71, v254, 10
	s_add_u32 s4, s70, s4
	s_addc_u32 s5, s71, 0
	s_lshl_b32 s7, s14, 2
	s_add_u32 s4, s4, s7
	s_addc_u32 s5, s5, 0
	v_mov_b32_e32 v191, v163
	v_mov_b32_e32 v72, 0
	v_lshl_or_b32 v134, s6, 12, v1
	s_mov_b64 s[100:101], s[4:5]
	v_lshl_add_u64 v[130:131], s[4:5], 0, v[190:191]
	s_mov_b32 s34, 0
	v_mov_b32_e32 v73, v72
	v_mov_b32_e32 v50, v72
	v_mov_b32_e32 v51, v72
	v_mov_b32_e32 v52, v72
	v_mov_b32_e32 v53, v72
	v_mov_b32_e32 v54, v72
	v_mov_b32_e32 v55, v72
	v_mov_b32_e32 v56, v72
	v_mov_b32_e32 v57, v72
	v_mov_b32_e32 v58, v72
	v_mov_b32_e32 v59, v72
	v_mov_b32_e32 v60, v72
	v_mov_b32_e32 v61, v72
	v_mov_b32_e32 v62, v72
	v_mov_b32_e32 v63, v72
	v_mov_b32_e32 v64, v72
	v_mov_b32_e32 v65, v72
	v_mov_b32_e32 v70, v72
	v_mov_b32_e32 v71, v72
	v_mov_b32_e32 v34, v72
	v_mov_b32_e32 v35, v72
	v_mov_b32_e32 v36, v72
	v_mov_b32_e32 v37, v72
	v_mov_b32_e32 v38, v72
	v_mov_b32_e32 v39, v72
	v_mov_b32_e32 v40, v72
	v_mov_b32_e32 v41, v72
	v_mov_b32_e32 v42, v72
	v_mov_b32_e32 v43, v72
	v_mov_b32_e32 v44, v72
	v_mov_b32_e32 v45, v72
	v_mov_b32_e32 v46, v72
	v_mov_b32_e32 v47, v72
	v_mov_b32_e32 v48, v72
	v_mov_b32_e32 v49, v72
	v_mov_b32_e32 v68, v72
	v_mov_b32_e32 v69, v72
	v_mov_b32_e32 v18, v72
	v_mov_b32_e32 v19, v72
	v_mov_b32_e32 v20, v72
	v_mov_b32_e32 v21, v72
	v_mov_b32_e32 v22, v72
	v_mov_b32_e32 v23, v72
	v_mov_b32_e32 v24, v72
	v_mov_b32_e32 v25, v72
	v_mov_b32_e32 v26, v72
	v_mov_b32_e32 v27, v72
	v_mov_b32_e32 v28, v72
	v_mov_b32_e32 v29, v72
	v_mov_b32_e32 v30, v72
	v_mov_b32_e32 v31, v72
	v_mov_b32_e32 v32, v72
	v_mov_b32_e32 v33, v72
	v_mov_b32_e32 v66, v72
	v_mov_b32_e32 v67, v72
	v_mov_b32_e32 v2, v72
	v_mov_b32_e32 v3, v72
	v_mov_b32_e32 v4, v72
	v_mov_b32_e32 v5, v72
	v_mov_b32_e32 v6, v72
	v_mov_b32_e32 v7, v72
	v_mov_b32_e32 v8, v72
	v_mov_b32_e32 v9, v72
	v_mov_b32_e32 v10, v72
	s_waitcnt lgkmcnt(0)
	v_mov_b32_e32 v11, v72
	v_mov_b32_e32 v12, v72
	v_mov_b32_e32 v13, v72
	v_mov_b32_e32 v14, v72
	v_mov_b32_e32 v15, v72
	v_mov_b32_e32 v16, v72
	v_mov_b32_e32 v17, v72
	v_readlane_b32 s65, v254, 4
	v_readlane_b32 s66, v254, 5
	v_readlane_b32 s67, v254, 6
	v_readlane_b32 s68, v254, 7
	v_readlane_b32 s69, v254, 8
	v_readlane_b32 s72, v254, 11
	v_readlane_b32 s73, v254, 12
	v_readlane_b32 s74, v254, 13
	v_readlane_b32 s75, v254, 14
	v_readlane_b32 s76, v254, 15
	v_readlane_b32 s77, v254, 16
	v_readlane_b32 s78, v254, 17
	v_readlane_b32 s79, v254, 18
	s_branch .LBB0_1521

; #define LAS __attribute__((address_space(3)))
; __device__ __forceinline__ f32x16 mma32(bf16x8 a, bf16x8 b, f32x16 c) { return __builtin_amdgcn_mfma_f32_32x32x16_bf16(a, b, c, 0, 0, 0); }
; __device__ __forceinline__ int acc_row(int reg, int hh) { return (reg & 3) + 8 * (reg >> 2) + 4 * hh; }
; __device__ __forceinline__ void gla_scan_task(const P& p, int l, int s, int h, int sl, LAS unsigned char* ldsw, int lane) {
;     ...
;         for (int ti = 0; ti < 2; ++ti) {
;             f32x16 o = zero16();
; #pragma unroll
;             for (int ks = 0; ks < 8; ++ks) { const bf16x8 b = *(const LAS bf16x8*)(ST + r * 136 + 16 * ks + 8 * hh); o = mma32(FRAG16(bufA, 4 + ti * 8 + ks, lane), b, o); }
; #pragma unroll
;             for (int ks = 0; ks < 4; ++ks) o = mma32(FRAG16(bufA, 20 + ti * 4 + ks, lane), vb[ks], o);
; #pragma unroll
;             for (int reg = 0; reg < 16; ++reg) p.OBRAW[(size_t)(r0 + 32 * ti + acc_row(reg, hh)) * 1024 + h * 256 + 32 * sl + r] = o[reg];
.LBB0_1532:
.LBB0_1543:
	s_waitcnt lgkmcnt(0)
	v_add_u32_e32 v172, v194, v148
	v_lshl_add_u32 v132, s34, 6, v134
	s_add_i32 s7, s34, 1
	v_ashrrev_i32_e32 v133, 31, v132
	v_lshlrev_b64 v[136:137], 12, v[132:133]
	v_lshl_add_u64 v[136:137], v[130:131], 0, v[136:137]
	ds_read_b128 v[94:97], v209 offset:16384
	ds_read_b128 v[90:93], v209 offset:17408
	ds_read_b128 v[86:89], v209 offset:18432
	ds_read_b128 v[82:85], v209 offset:19456
	ds_read_b128 v[122:125], v172
	ds_read_b128 v[236:239], v209 offset:20480
	ds_read_b128 v[118:121], v172 offset:32
	ds_read_b128 v[240:243], v209 offset:21504
	ds_read_b128 v[126:129], v172 offset:64
	ds_read_b128 v[244:247], v209 offset:22528
	ds_read_b128 v[114:117], v172 offset:96
	ds_read_b128 v[168:171], v209 offset:23552
	ds_read_b128 v[110:113], v172 offset:128
	ds_read_b128 v[212:215], v209 offset:24576
	s_waitcnt lgkmcnt(8)
	v_mfma_f32_32x32x16_bf16 v[66:81], v[236:239], v[122:125], 0
	ds_read_b128 v[106:109], v172 offset:160
	ds_read_b128 v[216:219], v209 offset:25600
	ds_read_b128 v[102:105], v172 offset:192
	ds_read_b128 v[220:223], v209 offset:26624
	s_waitcnt lgkmcnt(10)
	v_mfma_f32_32x32x16_bf16 v[66:81], v[240:243], v[118:121], v[66:81]
	ds_read_b128 v[98:101], v172 offset:224
	ds_read_b128 v[224:227], v209 offset:27648
	s_waitcnt lgkmcnt(10)
	v_mfma_f32_32x32x16_bf16 v[66:81], v[244:247], v[126:129], v[66:81]
	ds_read_b128 v[228:231], v209 offset:36864
	s_waitcnt lgkmcnt(9)
	v_mfma_f32_32x32x16_bf16 v[66:81], v[168:171], v[114:117], v[66:81]
	ds_read_b128 v[232:235], v209 offset:37888
	s_waitcnt lgkmcnt(8)
	v_mfma_f32_32x32x16_bf16 v[66:81], v[212:215], v[110:113], v[66:81]
	ds_read_b128 v[236:239], v209 offset:38912
	s_waitcnt lgkmcnt(7)
	v_mfma_f32_32x32x16_bf16 v[66:81], v[216:219], v[106:109], v[66:81]
	ds_read_b128 v[240:243], v209 offset:39936
	s_waitcnt lgkmcnt(6)
	v_mfma_f32_32x32x16_bf16 v[66:81], v[220:223], v[102:105], v[66:81]
	s_waitcnt lgkmcnt(4)
	v_mfma_f32_32x32x16_bf16 v[66:81], v[224:227], v[98:101], v[66:81]
	s_waitcnt lgkmcnt(3)
	v_mfma_f32_32x32x16_bf16 v[66:81], v[228:231], v[94:97], v[66:81]
	s_waitcnt lgkmcnt(2)
	v_mfma_f32_32x32x16_bf16 v[66:81], v[232:235], v[90:93], v[66:81]
	s_waitcnt lgkmcnt(1)
	v_mfma_f32_32x32x16_bf16 v[66:81], v[236:239], v[86:89], v[66:81]
	s_waitcnt lgkmcnt(0)
	v_mfma_f32_32x32x16_bf16 v[66:81], v[240:243], v[82:85], v[66:81]
	s_and_saveexec_b64 s[8:9], s[0:1]
	v_mov_b32_e32 v255, s7
	ds_write_b32 v163, v255 offset:13336
	s_or_b64 exec, exec, s[8:9]
	s_nop 11
	v_subrev_u32_e32 v137, s100, v130
	v_lshl_add_u32 v136, v132, 12, v137
	global_store_dword v136, v66, s[100:101]
	v_add_u32_e32 v136, 0x2000, v136
	global_store_dword v136, v67, s[100:101] offset:-4096
	global_store_dword v136, v68, s[100:101]
	v_add_u32_e32 v136, 0x1000, v136
	global_store_dword v136, v69, s[100:101]
	v_add_u32_e32 v136, 0x6000, v136
	global_store_dword v136, v70, s[100:101] offset:-4096
	global_store_dword v136, v71, s[100:101]
	v_add_u32_e32 v136, 0x2000, v136
	global_store_dword v136, v72, s[100:101] offset:-4096
	global_store_dword v136, v73, s[100:101]
	v_add_u32_e32 v136, 0x6000, v136
	global_store_dword v136, v74, s[100:101] offset:-4096
	global_store_dword v136, v75, s[100:101]
	v_add_u32_e32 v136, 0x2000, v136
	global_store_dword v136, v76, s[100:101] offset:-4096
	global_store_dword v136, v77, s[100:101]
	v_add_u32_e32 v136, 0x6000, v136
	global_store_dword v136, v78, s[100:101] offset:-4096
	global_store_dword v136, v79, s[100:101]
	v_add_u32_e32 v136, 0x2000, v136
	global_store_dword v136, v80, s[100:101] offset:-4096
	global_store_dword v136, v81, s[100:101]
	s_waitcnt lgkmcnt(0)
	ds_read_b32 v255, v163 offset:13316
	s_waitcnt lgkmcnt(0)
	v_cmp_lt_u32_e32 vcc, s34, v255
	s_cbranch_vccnz .Lgp1_done
	s_mov_b32 s4, 1
	s_branch .Lgp1_1535

; #define LAS __attribute__((address_space(3)))
; __device__ __forceinline__ f32x16 mma32(bf16x8 a, bf16x8 b, f32x16 c) { return __builtin_amdgcn_mfma_f32_32x32x16_bf16(a, b, c, 0, 0, 0); }
; __device__ __forceinline__ int acc_row(int reg, int hh) { return (reg & 3) + 8 * (reg >> 2) + 4 * hh; }
; #define LDS_WAIT() asm volatile("s_waitcnt lgkmcnt(0)" ::: "memory")
; __device__ __forceinline__ void gla_scan_task(const P& p, int l, int s, int h, int sl, LAS unsigned char* ldsw, int lane) {
;     ...
;         for (int ti = 0; ti < 2; ++ti) {
;             f32x16 o = zero16();
; #pragma unroll
;             for (int ks = 0; ks < 8; ++ks) { const bf16x8 b = *(const LAS bf16x8*)(ST + r * 136 + 16 * ks + 8 * hh); o = mma32(FRAG16(bufA, 4 + ti * 8 + ks, lane), b, o); }
; #pragma unroll
;             for (int ks = 0; ks < 4; ++ks) o = mma32(FRAG16(bufA, 20 + ti * 4 + ks, lane), vb[ks], o);
; #pragma unroll
;             for (int reg = 0; reg < 16; ++reg) p.OBRAW[(size_t)(r0 + 32 * ti + acc_row(reg, hh)) * 1024 + h * 256 + 32 * sl + r] = o[reg];
;         }
;         LDS_WAIT();
;         if (SCAN_LOADERS) { if (lane == 0) FL[3] = (unsigned)n + 1u; lds_wait_ge(FL + 2, (unsigned)n + 1u, FL + 5); }
.Lgp1_done:
	s_waitcnt lgkmcnt(0)
	ds_read_b128 v[236:239], v209 offset:28672
	ds_read_b128 v[240:243], v209 offset:29696
	ds_read_b128 v[244:247], v209 offset:30720
	ds_read_b128 v[168:171], v209 offset:31744
	ds_read_b128 v[212:215], v209 offset:32768
	ds_read_b128 v[216:219], v209 offset:33792
	s_waitcnt lgkmcnt(5)
	v_mfma_f32_32x32x16_bf16 v[66:81], v[236:239], v[122:125], 0
	ds_read_b128 v[220:223], v209 offset:34816
	s_waitcnt lgkmcnt(5)
	v_mfma_f32_32x32x16_bf16 v[66:81], v[240:243], v[118:121], v[66:81]
	ds_read_b128 v[224:227], v209 offset:35840
	s_waitcnt lgkmcnt(5)
	v_mfma_f32_32x32x16_bf16 v[66:81], v[244:247], v[126:129], v[66:81]
	ds_read_b128 v[228:231], v209 offset:40960
	s_waitcnt lgkmcnt(5)
	v_mfma_f32_32x32x16_bf16 v[66:81], v[168:171], v[114:117], v[66:81]
	ds_read_b128 v[232:235], v209 offset:41984
	s_waitcnt lgkmcnt(5)
	v_mfma_f32_32x32x16_bf16 v[66:81], v[212:215], v[110:113], v[66:81]
	ds_read_b128 v[236:239], v209 offset:43008
	s_waitcnt lgkmcnt(5)
	v_mfma_f32_32x32x16_bf16 v[66:81], v[216:219], v[106:109], v[66:81]
	ds_read_b128 v[240:243], v209 offset:44032
	s_waitcnt lgkmcnt(5)
	v_mfma_f32_32x32x16_bf16 v[66:81], v[220:223], v[102:105], v[66:81]
	s_waitcnt lgkmcnt(4)
	v_mfma_f32_32x32x16_bf16 v[66:81], v[224:227], v[98:101], v[66:81]
	s_waitcnt lgkmcnt(3)
	v_mfma_f32_32x32x16_bf16 v[66:81], v[228:231], v[94:97], v[66:81]
	s_waitcnt lgkmcnt(2)
	v_mfma_f32_32x32x16_bf16 v[66:81], v[232:235], v[90:93], v[66:81]
	s_waitcnt lgkmcnt(1)
	v_mfma_f32_32x32x16_bf16 v[66:81], v[236:239], v[86:89], v[66:81]
	s_waitcnt lgkmcnt(0)
	v_mfma_f32_32x32x16_bf16 v[66:81], v[240:243], v[82:85], v[66:81]
	s_and_saveexec_b64 s[8:9], s[0:1]
	v_mov_b32_e32 v255, s7
	ds_write_b32 v163, v255 offset:13324
	s_or_b64 exec, exec, s[8:9]
	s_nop 11
	v_subrev_u32_e32 v137, s100, v130
	v_lshl_add_u32 v136, v132, 12, v137
	v_add_u32_e32 v136, 0x21000, v136
	global_store_dword v136, v66, s[100:101] offset:-4096
	global_store_dword v136, v67, s[100:101]
	v_add_u32_e32 v136, 0x2000, v136
	global_store_dword v136, v68, s[100:101] offset:-4096
	global_store_dword v136, v69, s[100:101]
	v_add_u32_e32 v136, 0x6000, v136
	global_store_dword v136, v70, s[100:101] offset:-4096
	global_store_dword v136, v71, s[100:101]
	v_add_u32_e32 v136, 0x2000, v136
	global_store_dword v136, v72, s[100:101] offset:-4096
	global_store_dword v136, v73, s[100:101]
	v_add_u32_e32 v136, 0x6000, v136
	global_store_dword v136, v74, s[100:101] offset:-4096
	global_store_dword v136, v75, s[100:101]
	v_add_u32_e32 v136, 0x2000, v136
	global_store_dword v136, v76, s[100:101] offset:-4096
	global_store_dword v136, v77, s[100:101]
	v_add_u32_e32 v136, 0x6000, v136
	global_store_dword v136, v78, s[100:101] offset:-4096
	global_store_dword v136, v79, s[100:101]
	v_add_u32_e32 v136, 0x2000, v136
	global_store_dword v136, v80, s[100:101] offset:-4096
	global_store_dword v136, v81, s[100:101]
	s_waitcnt lgkmcnt(0)
	s_and_saveexec_b64 s[8:9], s[0:1]
	s_or_b64 exec, exec, s[8:9]
	ds_read_b32 v66, v163 offset:13320
	s_waitcnt lgkmcnt(0)
	v_cmp_lt_u32_e32 vcc, s34, v66
	s_cbranch_vccnz .LBB0_1556
	s_mov_b32 s4, 1
	s_branch .LBB0_1548
